# per-query selected loop: hand-written softmax step (all-far / unmasked / masked paths, bias reads batched, exp2 argument by one fma with the fp8 scale folded in)
# speedup vs baseline: 1.0309x; 1.0070x over previous
; #define LAS __attribute__((address_space(3)))
; __device__ __forceinline__ float fexp(float x) { return __expf(x); }
; template <int MODE>
; __device__ __forceinline__ void softmax_half(f32x4 (&acc)[2], int base, bool ok, int t, int g4, const LAS float* lutg, SmState& st, f32x4 (&O)[4], bf16x8& pB) {
;     float mx = -1e30f; unsigned vm = 0u;
; #pragma unroll
;     for (int nt = 0; nt < 2; ++nt)
; #pragma unroll
;         for (int i = 0; i < 4; ++i) {
;             const int key = base + 16 * nt + 4 * g4 + i;
;             const int dist = t - key;
;             bool valid = dist >= 0;
;             if (MODE == 1) valid = valid && ok;
;             if (MODE == 2) valid = valid && dist < 512;
;             int dc = dist < 0 ? 0 : dist; dc = dc > 1023 ? 1023 : dc;
;             const float lg = acc[nt][i] + lutg[dc * 4];
;             acc[nt][i] = lg;
;             if (valid) { mx = fmaxf(mx, lg); vm |= 1u << (nt * 4 + i); }
;         }
;     mx = fmaxf(mx, __shfl_xor(mx, 16)); mx = fmaxf(mx, __shfl_xor(mx, 32));
;     const float mn = fmaxf(st.m, mx);
;     const float sc = fexp(st.m - mn);
;     float ls = 0.f;
; #pragma unroll
;     for (int nt = 0; nt < 2; ++nt)
; #pragma unroll
;         for (int i = 0; i < 4; ++i) { const float p = ((vm >> (nt * 4 + i)) & 1u) ? fexp(acc[nt][i] - mn) : 0.f; acc[nt][i] = p; ls += p; }
;     st.l = st.l * sc + ls; st.m = mn;
; __device__ __forceinline__ void nsa_wave(CArgs* Ap, int l, int b, int g, int tq0, const LAS float* lut, LAS float* imp, int lane) {
;     ...
; #pragma unroll
;                 for (int q2 = 0; q2 < 4; ++q2) load_kh8(kq[q2], Ks8 + (size_t)jn[q2] * 4096, h1, lane); }
;             if (__all(jm >= 0 && t - (jm * 64 + 32 * hh + 31) >= 1023)) softmax_half_far(acc, lutg, st, Od);
;             else { bf16x8 pB; softmax_half<1>(acc, (jm < 0 ? 0 : jm) * 64 + 32 * hh, jm >= 0, t, g4, lutg, st, Od, pB); }
.Lsla_1271:
	s_and_b32 s50, s24, 32
	s_waitcnt lgkmcnt(0)
	v_mov_b32_e32 v165, v214
	v_lshl_or_b32 v150, v214, 6, s50
	v_sub_u32_e32 v150, v211, v150
	v_cmp_lt_i32_e32 vcc, -1, v214
	v_cmp_lt_i32_e64 s[48:49], s75, v150
	s_and_b64 s[48:49], vcc, s[48:49]
	s_cmp_eq_u64 s[48:49], exec
	s_cbranch_scc1 .Lsla_far
	v_max_i32_e32 v150, 0, v214
	v_lshlrev_b32_e32 v150, 6, v150
	v_or3_b32 v150, v150, s50, v88
	v_sub_u32_e32 v213, v72, v150
	v_cmp_lt_i32_e64 s[48:49], 18, v213
	s_and_b64 s[48:49], vcc, s[48:49]
	s_cmp_eq_u64 s[48:49], exec
	s_cbranch_scc1 .Lsla_um
	v_ashrrev_i32_e32 v216, 31, v214
	v_med3_i32 v151, v213, 0, v181
	v_lshl_add_u32 v151, v151, 4, v206
	ds_read_b32 v151, v151
	v_subrev_u32_e32 v215, 1, v213
	v_med3_i32 v215, v215, 0, v181
	v_lshl_add_u32 v215, v215, 4, v206
	ds_read_b32 v215, v215
	v_subrev_u32_e32 v218, 2, v213
	v_med3_i32 v218, v218, 0, v181
	v_lshl_add_u32 v218, v218, 4, v206
	ds_read_b32 v218, v218
	v_subrev_u32_e32 v219, 3, v213
	v_med3_i32 v219, v219, 0, v181
	v_lshl_add_u32 v219, v219, 4, v206
	ds_read_b32 v219, v219
	v_subrev_u32_e32 v220, 16, v213
	v_med3_i32 v220, v220, 0, v181
	v_lshl_add_u32 v220, v220, 4, v206
	ds_read_b32 v220, v220
	v_subrev_u32_e32 v221, 17, v213
	v_med3_i32 v221, v221, 0, v181
	v_lshl_add_u32 v221, v221, 4, v206
	ds_read_b32 v221, v221
	v_subrev_u32_e32 v222, 18, v213
	v_med3_i32 v222, v222, 0, v181
	v_lshl_add_u32 v222, v222, 4, v206
	ds_read_b32 v222, v222
	v_subrev_u32_e32 v150, 19, v213
	v_med3_i32 v150, v150, 0, v181
	v_lshl_add_u32 v150, v150, 4, v206
	ds_read_b32 v150, v150
	v_or_b32_e32 v216, v213, v216
	v_cmp_le_i32_e32 vcc, 0, v216
	v_cmp_le_i32_e64 s[48:49], 1, v216
	v_cmp_le_i32_e64 s[50:51], 2, v216
	v_cmp_le_i32_e64 s[52:53], 3, v216
	v_cmp_le_i32_e64 s[54:55], 16, v216
	v_cmp_le_i32_e64 s[56:57], 17, v216
	v_cmp_gt_i32_e64 s[58:59], 18, v216
	v_cmp_gt_i32_e64 s[60:61], 19, v216
	s_waitcnt lgkmcnt(7)
	v_add_f32_e32 v151, v24, v151
	v_max_f32_e32 v213, 0xf149f2ca, v151
	v_cndmask_b32_e32 v213, v182, v213, vcc
	s_waitcnt lgkmcnt(6)
	v_add_f32_e32 v215, v25, v215
	v_max_f32_e32 v217, v213, v215
	v_cndmask_b32_e64 v213, v213, v217, s[48:49]
	s_waitcnt lgkmcnt(5)
	v_add_f32_e32 v218, v26, v218
	v_max_f32_e32 v217, v213, v218
	v_cndmask_b32_e64 v213, v213, v217, s[50:51]
	s_waitcnt lgkmcnt(4)
	v_add_f32_e32 v219, v27, v219
	v_max_f32_e32 v217, v213, v219
	v_cndmask_b32_e64 v213, v213, v217, s[52:53]
	s_waitcnt lgkmcnt(3)
	v_add_f32_e32 v220, v28, v220
	v_max_f32_e32 v217, v213, v220
	v_cndmask_b32_e64 v213, v213, v217, s[54:55]
	s_waitcnt lgkmcnt(2)
	v_add_f32_e32 v221, v29, v221
	v_max_f32_e32 v217, v213, v221
	v_cndmask_b32_e64 v213, v213, v217, s[56:57]
	s_waitcnt lgkmcnt(1)
	v_add_f32_e32 v222, v30, v222
	v_max_f32_e32 v217, v213, v222
	v_cndmask_b32_e64 v213, v217, v213, s[58:59]
	s_waitcnt lgkmcnt(0)
	v_add_f32_e32 v150, v31, v150
	v_max_f32_e32 v217, v213, v150
	v_cndmask_b32_e64 v213, v217, v213, s[60:61]
	v_mov_b32_e32 v217, v213
	s_nop 1
	v_permlane16_swap_b32_e32 v213, v217
	v_max_f32_e32 v213, v213, v217
	v_mov_b32_e32 v217, v213
	s_nop 1
	v_permlane32_swap_b32_e32 v213, v217
	v_max3_f32 v213, v144, v213, v217
	v_mul_f32_e32 v214, 0xbfb8aa3b, v213
	v_add_f32_e32 v214, 0x41000000, v214
	v_fmamk_f32 v216, v151, 0x3fb8aa3b, v214
	v_fmamk_f32 v217, v215, 0x3fb8aa3b, v214
	v_fmamk_f32 v218, v218, 0x3fb8aa3b, v214
	v_fmamk_f32 v219, v219, 0x3fb8aa3b, v214
	v_fmamk_f32 v220, v220, 0x3fb8aa3b, v214
	v_fmamk_f32 v221, v221, 0x3fb8aa3b, v214
	v_fmamk_f32 v222, v222, 0x3fb8aa3b, v214
	v_fmamk_f32 v223, v150, 0x3fb8aa3b, v214
	v_exp_f32_e32 v216, v216
	v_exp_f32_e32 v217, v217
	v_exp_f32_e32 v218, v218
	v_exp_f32_e32 v219, v219
	v_exp_f32_e32 v220, v220
	v_exp_f32_e32 v221, v221
	v_exp_f32_e32 v222, v222
	v_exp_f32_e32 v223, v223
	v_cndmask_b32_e32 v216, 0, v216, vcc
	v_cndmask_b32_e64 v217, 0, v217, s[48:49]
	v_cndmask_b32_e64 v218, 0, v218, s[50:51]
	v_cndmask_b32_e64 v219, 0, v219, s[52:53]
	v_cndmask_b32_e64 v220, 0, v220, s[54:55]
	v_cndmask_b32_e64 v221, 0, v221, s[56:57]
	v_cndmask_b32_e64 v222, v222, 0, s[58:59]
	v_cndmask_b32_e64 v223, v223, 0, s[60:61]
	v_add_f32_e32 v151, v216, v217
	v_add_f32_e32 v215, v218, v219
	v_add_f32_e32 v150, v220, v221
	v_add_f32_e32 v214, v222, v223
	v_add_f32_e32 v151, v151, v215
	v_add_f32_e32 v150, v150, v214
	v_add_f32_e32 v151, v151, v150
	v_mul_f32_e32 v215, 0x3b800000, v151
	s_branch .Lsla_join
; __device__ __forceinline__ void softmax_half_far(f32x4 (&acc)[2], const LAS float* lutg, SmState& st, f32x4 (&O)[4]) {
;     const float bias = lutg[1023 * 4];
;     float mx = -1e30f;
; #pragma unroll
;     for (int nt = 0; nt < 2; ++nt)
; #pragma unroll
;         for (int i = 0; i < 4; ++i) { const float lg = acc[nt][i] + bias; acc[nt][i] = lg; mx = fmaxf(mx, lg); }
;     mx = fmaxf(mx, __shfl_xor(mx, 16)); mx = fmaxf(mx, __shfl_xor(mx, 32));
;     const float mn = fmaxf(st.m, mx);
;     const float sc = fexp(st.m - mn);
;     float ls = 0.f;
; #pragma unroll
;     for (int nt = 0; nt < 2; ++nt)
; #pragma unroll
;         for (int i = 0; i < 4; ++i) { const float p = fexp(acc[nt][i] - mn); acc[nt][i] = p; ls += p; }
;     st.l = st.l * sc + ls; st.m = mn;
; #pragma unroll
;     for (int dt = 0; dt < 4; ++dt) O[dt] = O[dt] * sc;
; }
; template <int MODE>
; __device__ __forceinline__ void softmax_half(f32x4 (&acc)[2], int base, bool ok, int t, int g4, const LAS float* lutg, SmState& st, f32x4 (&O)[4], bf16x8& pB) {
;     float mx = -1e30f; unsigned vm = 0u;
; #pragma unroll
;     for (int nt = 0; nt < 2; ++nt)
; #pragma unroll
;         for (int i = 0; i < 4; ++i) {
;             const int key = base + 16 * nt + 4 * g4 + i;
;             const int dist = t - key;
;             bool valid = dist >= 0;
;             if (MODE == 1) valid = valid && ok;
;             if (MODE == 2) valid = valid && dist < 512;
;             int dc = dist < 0 ? 0 : dist; dc = dc > 1023 ? 1023 : dc;
;             const float lg = acc[nt][i] + lutg[dc * 4];
;             acc[nt][i] = lg;
;             if (valid) { mx = fmaxf(mx, lg); vm |= 1u << (nt * 4 + i); }
;         }
;     mx = fmaxf(mx, __shfl_xor(mx, 16)); mx = fmaxf(mx, __shfl_xor(mx, 32));
;     const float mn = fmaxf(st.m, mx);
;     const float sc = fexp(st.m - mn);
;     float ls = 0.f;
; #pragma unroll
;     for (int nt = 0; nt < 2; ++nt)
; #pragma unroll
;         for (int i = 0; i < 4; ++i) { const float p = ((vm >> (nt * 4 + i)) & 1u) ? fexp(acc[nt][i] - mn) : 0.f; acc[nt][i] = p; ls += p; }
;     st.l = st.l * sc + ls; st.m = mn;
; #pragma unroll
;     for (int dt = 0; dt < 4; ++dt) O[dt] = O[dt] * sc;
;     u32x4 w; w.x = pk2(acc[0][0], acc[0][1]); w.y = pk2(acc[0][2], acc[0][3]); w.z = pk2(acc[1][0], acc[1][1]); w.w = pk2(acc[1][2], acc[1][3]);
;     pB = __builtin_bit_cast(bf16x8, w);
.Lsla_um:
	v_min_i32_e32 v151, v181, v213
	v_lshl_add_u32 v151, v151, 4, v206
	ds_read_b32 v151, v151
	v_subrev_u32_e32 v215, 1, v213
	v_min_i32_e32 v215, v181, v215
	v_lshl_add_u32 v215, v215, 4, v206
	ds_read_b32 v215, v215
	v_subrev_u32_e32 v150, 2, v213
	v_min_i32_e32 v150, v181, v150
	v_lshl_add_u32 v150, v150, 4, v206
	ds_read_b32 v150, v150
	v_subrev_u32_e32 v214, 3, v213
	v_min_i32_e32 v214, v181, v214
	v_lshl_add_u32 v214, v214, 4, v206
	ds_read_b32 v214, v214
	v_subrev_u32_e32 v216, 16, v213
	v_min_i32_e32 v216, v181, v216
	v_lshl_add_u32 v216, v216, 4, v206
	ds_read_b32 v216, v216
	v_subrev_u32_e32 v217, 17, v213
	v_min_i32_e32 v217, v181, v217
	v_lshl_add_u32 v217, v217, 4, v206
	ds_read_b32 v217, v217
	v_subrev_u32_e32 v218, 18, v213
	v_min_i32_e32 v218, v181, v218
	v_lshl_add_u32 v218, v218, 4, v206
	ds_read_b32 v218, v218
	v_subrev_u32_e32 v219, 19, v213
	v_min_i32_e32 v219, v181, v219
	v_lshl_add_u32 v219, v219, 4, v206
	ds_read_b32 v219, v219
	s_waitcnt lgkmcnt(7)
	v_add_f32_e32 v24, v24, v151
	s_waitcnt lgkmcnt(6)
	v_add_f32_e32 v25, v25, v215
	s_waitcnt lgkmcnt(5)
	v_add_f32_e32 v26, v26, v150
	s_waitcnt lgkmcnt(4)
	v_add_f32_e32 v27, v27, v214
	s_waitcnt lgkmcnt(3)
	v_add_f32_e32 v28, v28, v216
	s_waitcnt lgkmcnt(2)
	v_add_f32_e32 v29, v29, v217
	s_waitcnt lgkmcnt(1)
	v_add_f32_e32 v30, v30, v218
	s_waitcnt lgkmcnt(0)
	v_add_f32_e32 v31, v31, v219
	v_max3_f32 v213, v24, s74, v25
	v_max3_f32 v213, v213, v26, v27
	v_max3_f32 v213, v213, v28, v29
	v_max3_f32 v213, v213, v30, v31
	v_mov_b32_e32 v217, v213
	s_nop 1
	v_permlane16_swap_b32_e32 v213, v217
	v_max_f32_e32 v213, v213, v217
	v_mov_b32_e32 v217, v213
	s_nop 1
	v_permlane32_swap_b32_e32 v213, v217
	v_max3_f32 v213, v144, v213, v217
	v_mul_f32_e32 v214, 0xbfb8aa3b, v213
	v_add_f32_e32 v214, 0x41000000, v214
	v_fmamk_f32 v216, v24, 0x3fb8aa3b, v214
	v_fmamk_f32 v217, v25, 0x3fb8aa3b, v214
	v_fmamk_f32 v218, v26, 0x3fb8aa3b, v214
	v_fmamk_f32 v219, v27, 0x3fb8aa3b, v214
	v_fmamk_f32 v220, v28, 0x3fb8aa3b, v214
	v_fmamk_f32 v221, v29, 0x3fb8aa3b, v214
	v_fmamk_f32 v222, v30, 0x3fb8aa3b, v214
	v_fmamk_f32 v223, v31, 0x3fb8aa3b, v214
	v_exp_f32_e32 v216, v216
	v_exp_f32_e32 v217, v217
	v_exp_f32_e32 v218, v218
	v_exp_f32_e32 v219, v219
	v_exp_f32_e32 v220, v220
	v_exp_f32_e32 v221, v221
	v_exp_f32_e32 v222, v222
	v_exp_f32_e32 v223, v223
	v_add_f32_e32 v151, v216, v217
	v_add_f32_e32 v215, v218, v219
	v_add_f32_e32 v150, v220, v221
	v_add_f32_e32 v214, v222, v223
	v_add_f32_e32 v151, v151, v215
	v_add_f32_e32 v150, v150, v214
	v_add_f32_e32 v151, v151, v150
	v_mul_f32_e32 v215, 0x3b800000, v151
	s_branch .Lsla_join
.Lsla_far:
	v_add_f32_e32 v24, v24, v228
	v_add_f32_e32 v25, v25, v228
	v_add_f32_e32 v26, v26, v228
	v_add_f32_e32 v27, v27, v228
	v_add_f32_e32 v28, v28, v228
	v_add_f32_e32 v29, v29, v228
	v_add_f32_e32 v30, v30, v228
	v_add_f32_e32 v31, v31, v228
	v_max3_f32 v213, v24, s74, v25
	v_max3_f32 v213, v213, v26, v27
	v_max3_f32 v213, v213, v28, v29
	v_max3_f32 v213, v213, v30, v31
	v_mov_b32_e32 v217, v213
	s_nop 1
	v_permlane16_swap_b32_e32 v213, v217
	v_max_f32_e32 v213, v213, v217
	v_mov_b32_e32 v217, v213
	s_nop 1
	v_permlane32_swap_b32_e32 v213, v217
	v_max3_f32 v213, v144, v213, v217
	v_mul_f32_e32 v214, 0xbfb8aa3b, v213
	v_add_f32_e32 v214, 0x41000000, v214
	v_fmamk_f32 v216, v24, 0x3fb8aa3b, v214
	v_fmamk_f32 v217, v25, 0x3fb8aa3b, v214
	v_fmamk_f32 v218, v26, 0x3fb8aa3b, v214
	v_fmamk_f32 v219, v27, 0x3fb8aa3b, v214
	v_fmamk_f32 v220, v28, 0x3fb8aa3b, v214
	v_fmamk_f32 v221, v29, 0x3fb8aa3b, v214
	v_fmamk_f32 v222, v30, 0x3fb8aa3b, v214
	v_fmamk_f32 v223, v31, 0x3fb8aa3b, v214
	v_exp_f32_e32 v216, v216
	v_exp_f32_e32 v217, v217
	v_exp_f32_e32 v218, v218
	v_exp_f32_e32 v219, v219
	v_exp_f32_e32 v220, v220
	v_exp_f32_e32 v221, v221
	v_exp_f32_e32 v222, v222
	v_exp_f32_e32 v223, v223
	v_add_f32_e32 v151, v216, v217
	v_add_f32_e32 v215, v218, v219
	v_add_f32_e32 v150, v220, v221
	v_add_f32_e32 v214, v222, v223
	v_add_f32_e32 v151, v151, v215
	v_add_f32_e32 v150, v150, v214
	v_add_f32_e32 v151, v151, v150
	v_mul_f32_e32 v215, 0x3b800000, v151
.Lsla_join:
	v_sub_f32_e32 v24, v144, v213
	v_cvt_pk_fp8_f32 v31, v216, v217
	v_mul_f32_e32 v24, 0x3fb8aa3b, v24
	v_cvt_pk_fp8_f32 v144, v220, v221
	v_exp_f32_e32 v24, v24
	v_cvt_pk_fp8_f32 v31, v218, v219 op_sel:[0,0,1]
	v_cvt_pk_fp8_f32 v144, v222, v223 op_sel:[0,0,1]
	v_pk_mul_f32 v[22:23], v[22:23], v[24:25] op_sel_hi:[1,0]
	v_pk_mul_f32 v[20:21], v[20:21], v[24:25] op_sel_hi:[1,0]
	v_cndmask_b32_e64 v27, 0, v144, s[6:7]
	v_cndmask_b32_e64 v26, 0, v31, s[6:7]
	v_pk_mul_f32 v[18:19], v[18:19], v[24:25] op_sel_hi:[1,0]
	v_pk_mul_f32 v[16:17], v[16:17], v[24:25] op_sel_hi:[1,0]
	v_pk_mul_f32 v[14:15], v[14:15], v[24:25] op_sel_hi:[1,0]
	v_pk_mul_f32 v[12:13], v[12:13], v[24:25] op_sel_hi:[1,0]
	v_pk_mul_f32 v[10:11], v[10:11], v[24:25] op_sel_hi:[1,0]
	v_pk_mul_f32 v[8:9], v[8:9], v[24:25] op_sel_hi:[1,0]
	s_waitcnt vmcnt(31)
	s_nop 0
	v_mfma_f32_16x16x32_fp8_fp8 v[20:23], v[40:41], v[26:27], v[20:23]
	v_mfma_f32_16x16x32_fp8_fp8 v[16:19], v[42:43], v[26:27], v[16:19]
	s_waitcnt vmcnt(30)
	v_mfma_f32_16x16x32_fp8_fp8 v[12:15], v[44:45], v[26:27], v[12:15]
	v_mfma_f32_16x16x32_fp8_fp8 v[8:11], v[46:47], v[26:27], v[8:11]
	v_cndmask_b32_e64 v27, 0, v144, s[8:9]
	v_cndmask_b32_e64 v26, 0, v31, s[8:9]
	s_waitcnt vmcnt(29)
	s_nop 0
	v_mfma_f32_16x16x32_fp8_fp8 v[20:23], v[56:57], v[26:27], v[20:23]
	v_mfma_f32_16x16x32_fp8_fp8 v[16:19], v[58:59], v[26:27], v[16:19]
	s_waitcnt vmcnt(28)
	v_mfma_f32_16x16x32_fp8_fp8 v[12:15], v[60:61], v[26:27], v[12:15]
	v_mfma_f32_16x16x32_fp8_fp8 v[8:11], v[62:63], v[26:27], v[8:11]
	v_cndmask_b32_e64 v27, 0, v144, s[10:11]
	v_cndmask_b32_e64 v26, 0, v31, s[10:11]
	s_waitcnt vmcnt(27)
; __device__ __forceinline__ void nsa_wave(CArgs* Ap, int l, int b, int g, int tq0, const LAS float* lut, LAS float* imp, int lane) {
;     ...
;         for (int hs = h0; hs < nh; ++hs) {
;             const int s = hs >> 1, hh = hs & 1;
;             const int jm = __shfl(selreg, 16 * qi + s);
;             f32x4 acc[2];
;             acc[0] = (f32x4){0.f, 0.f, 0.f, 0.f}; acc[1] = (f32x4){0.f, 0.f, 0.f, 0.f};
; #pragma unroll
;             for (int q2 = 0; q2 < 4; ++q2) { long qm[2]; qm[0] = (qi == q2) ? q8[0] : 0l; qm[1] = (qi == q2) ? q8[1] : 0l; qk_acch8(acc, kq[q2], qm); }
;             const bool more = hs + 1 < nh; const int s1 = (hs + 1) >> 1, h1 = (hs + 1) & 1;
;             int jn[4];
; #pragma unroll
;             for (int q2 = 0; q2 < 4; ++q2) { int j = more ? __builtin_amdgcn_readlane(selreg, 16 * q2 + s1) : 0; jn[q2] = j < 0 ? 0 : j; }
;             if (more) {
; #pragma unroll
;                 for (int q2 = 0; q2 < 4; ++q2) load_kh8(kq[q2], Ks8 + (size_t)jn[q2] * 4096, h1, lane); }
;             if (__all(jm >= 0 && t - (jm * 64 + 32 * hh + 31) >= 1023)) softmax_half_far(acc, lutg, st, Od);
;             else { bf16x8 pB; softmax_half<1>(acc, (jm < 0 ? 0 : jm) * 64 + 32 * hh, jm >= 0, t, g4, lutg, st, Od, pB); }
;             const long p8 = p_to_fp8(acc);
; #pragma unroll
;             for (int q2 = 0; q2 < 4; ++q2) { const long pm = (qi == q2) ? p8 : 0l; pv_acch8(Od, vq[q2], pm); }
;             if (more) {
; #pragma unroll
;                 for (int q2 = 0; q2 < 4; ++q2) load_vh8(vq[q2], Vs8 + (size_t)jn[q2] * 4096, h1, lane); }
	s_nop 0
	v_mfma_f32_16x16x32_fp8_fp8 v[20:23], v[74:75], v[26:27], v[20:23]
	v_mfma_f32_16x16x32_fp8_fp8 v[16:19], v[76:77], v[26:27], v[16:19]
	s_waitcnt vmcnt(26)
	v_mfma_f32_16x16x32_fp8_fp8 v[12:15], v[78:79], v[26:27], v[12:15]
	v_mfma_f32_16x16x32_fp8_fp8 v[8:11], v[80:81], v[26:27], v[8:11]
	v_cndmask_b32_e64 v27, 0, v144, s[12:13]
	v_cndmask_b32_e64 v26, 0, v31, s[12:13]
	s_waitcnt vmcnt(25)
	s_nop 0
	v_mfma_f32_16x16x32_fp8_fp8 v[20:23], v[106:107], v[26:27], v[20:23]
	v_mfma_f32_16x16x32_fp8_fp8 v[16:19], v[108:109], v[26:27], v[16:19]
	s_waitcnt vmcnt(24)
	v_mfma_f32_16x16x32_fp8_fp8 v[12:15], v[122:123], v[26:27], v[12:15]
	v_mfma_f32_16x16x32_fp8_fp8 v[8:11], v[124:125], v[26:27], v[8:11]
	s_add_u32 s48, s0, s26
	s_addc_u32 s49, s1, s27
	global_load_dwordx4 v[40:43], v84, s[48:49]
	global_load_dwordx4 v[44:47], v84, s[48:49] offset:1024
	s_add_u32 s48, s0, s28
	s_addc_u32 s49, s1, s29
	global_load_dwordx4 v[56:59], v84, s[48:49]
	global_load_dwordx4 v[60:63], v84, s[48:49] offset:1024
	s_add_u32 s48, s0, s30
	s_addc_u32 s49, s1, s31
	global_load_dwordx4 v[74:77], v84, s[48:49]
	global_load_dwordx4 v[78:81], v84, s[48:49] offset:1024
	s_add_u32 s48, s0, s34
	s_addc_u32 s49, s1, s35
	global_load_dwordx4 v[106:109], v84, s[48:49]
	global_load_dwordx4 v[122:125], v84, s[48:49] offset:1024
	v_fmac_f32_e32 v215, v212, v24
	s_add_i32 s24, s24, 32
	s_nop 0
	v_mov_b32_e32 v212, v215
	v_mov_b32_e32 v144, v213
	s_waitcnt vmcnt(31)
	v_mfma_f32_16x16x32_fp8_fp8 v[24:27], v[184:185], v[82:83], 0
	v_mov_b32_e32 v214, v165
	s_nop 0
	s_waitcnt vmcnt(30)
	v_mfma_f32_16x16x32_fp8_fp8 v[28:31], v[188:189], v[82:83], 0
	s_nop 0
	s_nop 0
	v_mfma_f32_16x16x32_fp8_fp8 v[24:27], v[186:187], v[104:105], v[24:27]
	v_mfma_f32_16x16x32_fp8_fp8 v[28:31], v[190:191], v[104:105], v[28:31]
	s_waitcnt vmcnt(29)
	v_mfma_f32_16x16x32_fp8_fp8 v[24:27], v[192:193], v[98:99], v[24:27]
	s_waitcnt vmcnt(28)
	v_mfma_f32_16x16x32_fp8_fp8 v[28:31], v[196:197], v[98:99], v[28:31]
	v_mfma_f32_16x16x32_fp8_fp8 v[24:27], v[194:195], v[110:111], v[24:27]
	v_mfma_f32_16x16x32_fp8_fp8 v[28:31], v[198:199], v[110:111], v[28:31]
	s_waitcnt vmcnt(27)
	v_mfma_f32_16x16x32_fp8_fp8 v[24:27], v[230:231], v[100:101], v[24:27]
	s_waitcnt vmcnt(26)
	v_mfma_f32_16x16x32_fp8_fp8 v[28:31], v[234:235], v[100:101], v[28:31]
	v_mfma_f32_16x16x32_fp8_fp8 v[24:27], v[232:233], v[120:121], v[24:27]
	v_mfma_f32_16x16x32_fp8_fp8 v[28:31], v[236:237], v[120:121], v[28:31]
	s_waitcnt vmcnt(25)
	v_mfma_f32_16x16x32_fp8_fp8 v[24:27], v[238:239], v[102:103], v[24:27]
	s_waitcnt vmcnt(24)
	v_mfma_f32_16x16x32_fp8_fp8 v[28:31], v[242:243], v[102:103], v[28:31]
	v_mfma_f32_16x16x32_fp8_fp8 v[24:27], v[240:241], v[126:127], v[24:27]
	v_mfma_f32_16x16x32_fp8_fp8 v[28:31], v[244:245], v[126:127], v[28:31]
	s_add_u32 s48, s96, s26
	s_addc_u32 s49, s97, s27
	global_load_dwordx4 v[184:187], v229, s[48:49]
	global_load_dwordx4 v[188:191], v229, s[48:49] offset:1024
	s_add_u32 s48, s96, s28
	s_addc_u32 s49, s97, s29
	global_load_dwordx4 v[192:195], v229, s[48:49]
	global_load_dwordx4 v[196:199], v229, s[48:49] offset:1024
	s_add_u32 s48, s96, s30
	s_addc_u32 s49, s97, s31
	global_load_dwordx4 v[230:233], v229, s[48:49]
	global_load_dwordx4 v[234:237], v229, s[48:49] offset:1024
	s_add_u32 s48, s96, s34
	s_addc_u32 s49, s97, s35
	global_load_dwordx4 v[238:241], v229, s[48:49]
	global_load_dwordx4 v[242:245], v229, s[48:49] offset:1024
; #define LAS __attribute__((address_space(3)))
; __device__ __forceinline__ unsigned pk2(float lo, float hi) { return pg8::cvt_pk_bf16(lo, hi); }
; __device__ __forceinline__ float fexp(float x) { return __expf(x); }
; template <int MODE>
; __device__ __forceinline__ void softmax_half(f32x4 (&acc)[2], int base, bool ok, int t, int g4, const LAS float* lutg, SmState& st, f32x4 (&O)[4], bf16x8& pB) {
;     float mx = -1e30f; unsigned vm = 0u;
; #pragma unroll
;     for (int nt = 0; nt < 2; ++nt)
; #pragma unroll
;         for (int i = 0; i < 4; ++i) {
;             const int key = base + 16 * nt + 4 * g4 + i;
;             const int dist = t - key;
;             bool valid = dist >= 0;
;             if (MODE == 1) valid = valid && ok;
;             if (MODE == 2) valid = valid && dist < 512;
;             int dc = dist < 0 ? 0 : dist; dc = dc > 1023 ? 1023 : dc;
;             const float lg = acc[nt][i] + lutg[dc * 4];
;             acc[nt][i] = lg;
;             if (valid) { mx = fmaxf(mx, lg); vm |= 1u << (nt * 4 + i); }
;         }
;     mx = fmaxf(mx, __shfl_xor(mx, 16)); mx = fmaxf(mx, __shfl_xor(mx, 32));
;     const float mn = fmaxf(st.m, mx);
;     const float sc = fexp(st.m - mn);
;     float ls = 0.f;
; #pragma unroll
;     for (int nt = 0; nt < 2; ++nt)
; #pragma unroll
;         for (int i = 0; i < 4; ++i) { const float p = ((vm >> (nt * 4 + i)) & 1u) ? fexp(acc[nt][i] - mn) : 0.f; acc[nt][i] = p; ls += p; }
;     st.l = st.l * sc + ls; st.m = mn;
; #pragma unroll
;     for (int dt = 0; dt < 4; ++dt) O[dt] = O[dt] * sc;
;     u32x4 w; w.x = pk2(acc[0][0], acc[0][1]); w.y = pk2(acc[0][2], acc[0][3]); w.z = pk2(acc[1][0], acc[1][1]); w.w = pk2(acc[1][2], acc[1][3]);
;     pB = __builtin_bit_cast(bf16x8, w);
; }
; __device__ __forceinline__ void nsa_wave(CArgs* Ap, int l, int b, int g, int tq0, const LAS float* lut, LAS float* imp, int lane) {
;     ...
;             if (__all(jm >= 0 && t - (jm * 64 + 32 * hh + 31) >= 1023)) softmax_half_far(acc, lutg, st, Od);
;             else { bf16x8 pB; softmax_half<1>(acc, (jm < 0 ? 0 : jm) * 64 + 32 * hh, jm >= 0, t, g4, lutg, st, Od, pB); }
.Lslb_1271:
	s_and_b32 s50, s24, 32
	s_waitcnt lgkmcnt(0)
	v_lshl_or_b32 v150, v214, 6, s50
	v_sub_u32_e32 v150, v211, v150
	v_cmp_lt_i32_e32 vcc, -1, v214
	v_cmp_lt_i32_e64 s[48:49], s75, v150
	s_and_b64 s[48:49], vcc, s[48:49]
	s_cmp_eq_u64 s[48:49], exec
	s_cbranch_scc1 .Lslb_far
	v_max_i32_e32 v150, 0, v214
	v_lshlrev_b32_e32 v150, 6, v150
	v_or3_b32 v150, v150, s50, v88
	v_sub_u32_e32 v213, v72, v150
	v_cmp_lt_i32_e64 s[48:49], 18, v213
	s_and_b64 s[48:49], vcc, s[48:49]
	s_cmp_eq_u64 s[48:49], exec
	s_cbranch_scc1 .Lslb_um
	v_ashrrev_i32_e32 v216, 31, v214
	v_med3_i32 v151, v213, 0, v181
	v_lshl_add_u32 v151, v151, 4, v206
	ds_read_b32 v151, v151
	v_subrev_u32_e32 v215, 1, v213
	v_med3_i32 v215, v215, 0, v181
	v_lshl_add_u32 v215, v215, 4, v206
	ds_read_b32 v215, v215
	v_subrev_u32_e32 v218, 2, v213
	v_med3_i32 v218, v218, 0, v181
	v_lshl_add_u32 v218, v218, 4, v206
	ds_read_b32 v218, v218
	v_subrev_u32_e32 v219, 3, v213
	v_med3_i32 v219, v219, 0, v181
	v_lshl_add_u32 v219, v219, 4, v206
	ds_read_b32 v219, v219
	v_subrev_u32_e32 v220, 16, v213
	v_med3_i32 v220, v220, 0, v181
	v_lshl_add_u32 v220, v220, 4, v206
	ds_read_b32 v220, v220
	v_subrev_u32_e32 v221, 17, v213
	v_med3_i32 v221, v221, 0, v181
	v_lshl_add_u32 v221, v221, 4, v206
	ds_read_b32 v221, v221
	v_subrev_u32_e32 v222, 18, v213
	v_med3_i32 v222, v222, 0, v181
	v_lshl_add_u32 v222, v222, 4, v206
	ds_read_b32 v222, v222
	v_subrev_u32_e32 v150, 19, v213
	v_med3_i32 v150, v150, 0, v181
	v_lshl_add_u32 v150, v150, 4, v206
	ds_read_b32 v150, v150
	v_or_b32_e32 v216, v213, v216
	v_cmp_le_i32_e32 vcc, 0, v216
	v_cmp_le_i32_e64 s[48:49], 1, v216
	v_cmp_le_i32_e64 s[50:51], 2, v216
	v_cmp_le_i32_e64 s[52:53], 3, v216
	v_cmp_le_i32_e64 s[54:55], 16, v216
	v_cmp_le_i32_e64 s[56:57], 17, v216
	v_cmp_gt_i32_e64 s[58:59], 18, v216
	v_cmp_gt_i32_e64 s[60:61], 19, v216
	s_waitcnt lgkmcnt(7)
	v_add_f32_e32 v151, v24, v151
	v_max_f32_e32 v213, 0xf149f2ca, v151
	v_cndmask_b32_e32 v213, v182, v213, vcc
	s_waitcnt lgkmcnt(6)
	v_add_f32_e32 v215, v25, v215
	v_max_f32_e32 v217, v213, v215
	v_cndmask_b32_e64 v213, v213, v217, s[48:49]
	s_waitcnt lgkmcnt(5)
	v_add_f32_e32 v218, v26, v218
	v_max_f32_e32 v217, v213, v218
	v_cndmask_b32_e64 v213, v213, v217, s[50:51]
	s_waitcnt lgkmcnt(4)
	v_add_f32_e32 v219, v27, v219
	v_max_f32_e32 v217, v213, v219
	v_cndmask_b32_e64 v213, v213, v217, s[52:53]
	s_waitcnt lgkmcnt(3)
	v_add_f32_e32 v220, v28, v220
	v_max_f32_e32 v217, v213, v220
	v_cndmask_b32_e64 v213, v213, v217, s[54:55]
	s_waitcnt lgkmcnt(2)
	v_add_f32_e32 v221, v29, v221
	v_max_f32_e32 v217, v213, v221
	v_cndmask_b32_e64 v213, v213, v217, s[56:57]
	s_waitcnt lgkmcnt(1)
	v_add_f32_e32 v222, v30, v222
	v_max_f32_e32 v217, v213, v222
	v_cndmask_b32_e64 v213, v217, v213, s[58:59]
	s_waitcnt lgkmcnt(0)
	v_add_f32_e32 v150, v31, v150
	v_max_f32_e32 v217, v213, v150
	v_cndmask_b32_e64 v213, v217, v213, s[60:61]
	v_mov_b32_e32 v217, v213
	s_nop 1
	v_permlane16_swap_b32_e32 v213, v217
	v_max_f32_e32 v213, v213, v217
	v_mov_b32_e32 v217, v213
	s_nop 1
	v_permlane32_swap_b32_e32 v213, v217
	v_max3_f32 v213, v144, v213, v217
	v_mul_f32_e32 v214, 0xbfb8aa3b, v213
	v_add_f32_e32 v214, 0x41000000, v214
	v_fmamk_f32 v216, v151, 0x3fb8aa3b, v214
	v_fmamk_f32 v217, v215, 0x3fb8aa3b, v214
	v_fmamk_f32 v218, v218, 0x3fb8aa3b, v214
	v_fmamk_f32 v219, v219, 0x3fb8aa3b, v214
	v_fmamk_f32 v220, v220, 0x3fb8aa3b, v214
	v_fmamk_f32 v221, v221, 0x3fb8aa3b, v214
	v_fmamk_f32 v222, v222, 0x3fb8aa3b, v214
	v_fmamk_f32 v223, v150, 0x3fb8aa3b, v214
	v_exp_f32_e32 v216, v216
	v_exp_f32_e32 v217, v217
	v_exp_f32_e32 v218, v218
	v_exp_f32_e32 v219, v219
	v_exp_f32_e32 v220, v220
	v_exp_f32_e32 v221, v221
	v_exp_f32_e32 v222, v222
	v_exp_f32_e32 v223, v223
	v_cndmask_b32_e32 v216, 0, v216, vcc
	v_cndmask_b32_e64 v217, 0, v217, s[48:49]
	v_cndmask_b32_e64 v218, 0, v218, s[50:51]
	v_cndmask_b32_e64 v219, 0, v219, s[52:53]
	v_cndmask_b32_e64 v220, 0, v220, s[54:55]
	v_cndmask_b32_e64 v221, 0, v221, s[56:57]
	v_cndmask_b32_e64 v222, v222, 0, s[58:59]
	v_cndmask_b32_e64 v223, v223, 0, s[60:61]
	v_add_f32_e32 v151, v216, v217
	v_add_f32_e32 v215, v218, v219
	v_add_f32_e32 v150, v220, v221
	v_add_f32_e32 v214, v222, v223
	v_add_f32_e32 v151, v151, v215
	v_add_f32_e32 v150, v150, v214
	v_add_f32_e32 v151, v151, v150
	v_mul_f32_e32 v215, 0x3b800000, v151
	s_branch .Lslb_join

; __device__ __forceinline__ unsigned pk2(float lo, float hi) { return pg8::cvt_pk_bf16(lo, hi); }
; template <int MODE>
; __device__ __forceinline__ void softmax_half(f32x4 (&acc)[2], int base, bool ok, int t, int g4, const LAS float* lutg, SmState& st, f32x4 (&O)[4], bf16x8& pB) {
;     ...
;     st.l = st.l * sc + ls; st.m = mn;
; #pragma unroll
;     for (int dt = 0; dt < 4; ++dt) O[dt] = O[dt] * sc;
;     u32x4 w; w.x = pk2(acc[0][0], acc[0][1]); w.y = pk2(acc[0][2], acc[0][3]); w.z = pk2(acc[1][0], acc[1][1]); w.w = pk2(acc[1][2], acc[1][3]);
;     pB = __builtin_bit_cast(bf16x8, w);
; __device__ __forceinline__ void nsa_wave(CArgs* Ap, int l, int b, int g, int tq0, const LAS float* lut, LAS float* imp, int lane) {
;     ...
;             const long p8 = p_to_fp8(acc);
; #pragma unroll
;             for (int q2 = 0; q2 < 4; ++q2) { const long pm = (qi == q2) ? p8 : 0l; pv_acch8(Od, vq[q2], pm); }
;             if (more) {
; #pragma unroll
;                 for (int q2 = 0; q2 < 4; ++q2) load_vh8(vq[q2], Vs8 + (size_t)jn[q2] * 4096, h1, lane); }
;         }
.Lslb_join:
	v_sub_f32_e32 v24, v144, v213
	v_cvt_pk_fp8_f32 v31, v216, v217
	v_mul_f32_e32 v24, 0x3fb8aa3b, v24
	v_cvt_pk_fp8_f32 v144, v220, v221
	v_exp_f32_e32 v24, v24
	v_cvt_pk_fp8_f32 v31, v218, v219 op_sel:[0,0,1]
	v_cvt_pk_fp8_f32 v144, v222, v223 op_sel:[0,0,1]
	v_pk_mul_f32 v[22:23], v[22:23], v[24:25] op_sel_hi:[1,0]
	v_pk_mul_f32 v[20:21], v[20:21], v[24:25] op_sel_hi:[1,0]
	v_cndmask_b32_e64 v27, 0, v144, s[6:7]
	v_cndmask_b32_e64 v26, 0, v31, s[6:7]
	v_pk_mul_f32 v[18:19], v[18:19], v[24:25] op_sel_hi:[1,0]
	v_pk_mul_f32 v[16:17], v[16:17], v[24:25] op_sel_hi:[1,0]
	v_pk_mul_f32 v[14:15], v[14:15], v[24:25] op_sel_hi:[1,0]
	v_pk_mul_f32 v[12:13], v[12:13], v[24:25] op_sel_hi:[1,0]
	v_pk_mul_f32 v[10:11], v[10:11], v[24:25] op_sel_hi:[1,0]
	v_pk_mul_f32 v[8:9], v[8:9], v[24:25] op_sel_hi:[1,0]
	s_waitcnt vmcnt(31)
	s_nop 0
	v_mfma_f32_16x16x32_fp8_fp8 v[20:23], v[134:135], v[26:27], v[20:23]
	v_mfma_f32_16x16x32_fp8_fp8 v[16:19], v[136:137], v[26:27], v[16:19]
	s_waitcnt vmcnt(30)
	v_mfma_f32_16x16x32_fp8_fp8 v[12:15], v[138:139], v[26:27], v[12:15]
	v_mfma_f32_16x16x32_fp8_fp8 v[8:11], v[140:141], v[26:27], v[8:11]
	v_cndmask_b32_e64 v27, 0, v144, s[8:9]
	v_cndmask_b32_e64 v26, 0, v31, s[8:9]
	s_waitcnt vmcnt(29)
	s_nop 0
	v_mfma_f32_16x16x32_fp8_fp8 v[20:23], v[152:153], v[26:27], v[20:23]
	v_mfma_f32_16x16x32_fp8_fp8 v[16:19], v[154:155], v[26:27], v[16:19]
	s_waitcnt vmcnt(28)
	v_mfma_f32_16x16x32_fp8_fp8 v[12:15], v[156:157], v[26:27], v[12:15]
	v_mfma_f32_16x16x32_fp8_fp8 v[8:11], v[158:159], v[26:27], v[8:11]
	v_cndmask_b32_e64 v27, 0, v144, s[10:11]
	v_cndmask_b32_e64 v26, 0, v31, s[10:11]
	s_waitcnt vmcnt(27)
	s_nop 0
	v_mfma_f32_16x16x32_fp8_fp8 v[20:23], v[160:161], v[26:27], v[20:23]
	v_mfma_f32_16x16x32_fp8_fp8 v[16:19], v[162:163], v[26:27], v[16:19]
	s_waitcnt vmcnt(26)
	v_mfma_f32_16x16x32_fp8_fp8 v[12:15], v[246:247], v[26:27], v[12:15]
	v_mfma_f32_16x16x32_fp8_fp8 v[8:11], v[248:249], v[26:27], v[8:11]
	v_cndmask_b32_e64 v27, 0, v144, s[12:13]
	v_cndmask_b32_e64 v26, 0, v31, s[12:13]
	s_waitcnt vmcnt(25)
	s_nop 0
	v_mfma_f32_16x16x32_fp8_fp8 v[20:23], v[0:1], v[26:27], v[20:23]
	v_mfma_f32_16x16x32_fp8_fp8 v[16:19], v[2:3], v[26:27], v[16:19]
	s_waitcnt vmcnt(24)
	v_mfma_f32_16x16x32_fp8_fp8 v[12:15], v[4:5], v[26:27], v[12:15]
	v_mfma_f32_16x16x32_fp8_fp8 v[8:11], v[6:7], v[26:27], v[8:11]
	s_add_u32 s48, s0, s26
	s_addc_u32 s49, s1, s27
	global_load_dwordx4 v[134:137], v229, s[48:49]
	global_load_dwordx4 v[138:141], v229, s[48:49] offset:1024
	s_add_u32 s48, s0, s28
	s_addc_u32 s49, s1, s29
	global_load_dwordx4 v[152:155], v229, s[48:49]
	global_load_dwordx4 v[156:159], v229, s[48:49] offset:1024
	s_add_u32 s48, s0, s30
	s_addc_u32 s49, s1, s31
	global_load_dwordx4 v[160:163], v229, s[48:49]
	global_load_dwordx4 v[246:249], v229, s[48:49] offset:1024
	s_add_u32 s48, s0, s34
	s_addc_u32 s49, s1, s35
	global_load_dwordx4 v[0:3], v229, s[48:49]
	global_load_dwordx4 v[4:7], v229, s[48:49] offset:1024
	v_fmac_f32_e32 v215, v212, v24
	s_add_i32 s24, s24, 32
	s_nop 0
	v_mov_b32_e32 v212, v215
	v_mov_b32_e32 v144, v213
	s_add_i32 s32, s32, 1
	s_mov_b64 s[36:37], s[26:27]
	s_mov_b64 s[38:39], s[28:29]
	s_mov_b64 s[40:41], s[30:31]
	s_mov_b64 s[84:85], s[34:35]
	s_add_i32 s25, s32, 1
	s_cmp_lt_i32 s25, s42
	s_cbranch_scc1 .Lsl_steady

; __device__ __forceinline__ void nsa_wave(CArgs* Ap, int l, int b, int g, int tq0, const LAS float* lut, LAS float* imp, int lane) {
;     ...
;         for (int hs = h0; hs < nh; ++hs) {
;             const int s = hs >> 1, hh = hs & 1;
;             const int jm = __shfl(selreg, 16 * qi + s);
;             f32x4 acc[2];
;             acc[0] = (f32x4){0.f, 0.f, 0.f, 0.f}; acc[1] = (f32x4){0.f, 0.f, 0.f, 0.f};
; #pragma unroll
;             for (int q2 = 0; q2 < 4; ++q2) { long qm[2]; qm[0] = (qi == q2) ? q8[0] : 0l; qm[1] = (qi == q2) ? q8[1] : 0l; qk_acch8(acc, kq[q2], qm); }
;             const bool more = hs + 1 < nh; const int s1 = (hs + 1) >> 1, h1 = (hs + 1) & 1;
;             int jn[4];
; #pragma unroll
;             for (int q2 = 0; q2 < 4; ++q2) { int j = more ? __builtin_amdgcn_readlane(selreg, 16 * q2 + s1) : 0; jn[q2] = j < 0 ? 0 : j; }
;             if (more) {
; #pragma unroll
;                 for (int q2 = 0; q2 < 4; ++q2) load_kh8(kq[q2], Ks8 + (size_t)jn[q2] * 4096, h1, lane); }
;             if (__all(jm >= 0 && t - (jm * 64 + 32 * hh + 31) >= 1023)) softmax_half_far(acc, lutg, st, Od);
;             else { bf16x8 pB; softmax_half<1>(acc, (jm < 0 ? 0 : jm) * 64 + 32 * hh, jm >= 0, t, g4, lutg, st, Od, pB); }
;             const long p8 = p_to_fp8(acc);
; #pragma unroll
;             for (int q2 = 0; q2 < 4; ++q2) { const long pm = (qi == q2) ? p8 : 0l; pv_acch8(Od, vq[q2], pm); }
;             if (more) {
; #pragma unroll
;                 for (int q2 = 0; q2 < 4; ++q2) load_vh8(vq[q2], Vs8 + (size_t)jn[q2] * 4096, h1, lane); }
;         }
.Lslc_join:
	v_sub_f32_e32 v24, v144, v213
	v_cvt_pk_fp8_f32 v31, v216, v217
	v_mul_f32_e32 v24, 0x3fb8aa3b, v24
	v_cvt_pk_fp8_f32 v144, v220, v221
	v_exp_f32_e32 v24, v24
	v_cvt_pk_fp8_f32 v31, v218, v219 op_sel:[0,0,1]
	v_cvt_pk_fp8_f32 v144, v222, v223 op_sel:[0,0,1]
	v_pk_mul_f32 v[22:23], v[22:23], v[24:25] op_sel_hi:[1,0]
	v_pk_mul_f32 v[20:21], v[20:21], v[24:25] op_sel_hi:[1,0]
	v_cndmask_b32_e64 v27, 0, v144, s[6:7]
	v_cndmask_b32_e64 v26, 0, v31, s[6:7]
	v_pk_mul_f32 v[18:19], v[18:19], v[24:25] op_sel_hi:[1,0]
	v_pk_mul_f32 v[16:17], v[16:17], v[24:25] op_sel_hi:[1,0]
	v_pk_mul_f32 v[14:15], v[14:15], v[24:25] op_sel_hi:[1,0]
	v_pk_mul_f32 v[12:13], v[12:13], v[24:25] op_sel_hi:[1,0]
	v_pk_mul_f32 v[10:11], v[10:11], v[24:25] op_sel_hi:[1,0]
	v_pk_mul_f32 v[8:9], v[8:9], v[24:25] op_sel_hi:[1,0]
	s_waitcnt vmcnt(23)
	s_nop 0
	v_mfma_f32_16x16x32_fp8_fp8 v[20:23], v[40:41], v[26:27], v[20:23]
	v_mfma_f32_16x16x32_fp8_fp8 v[16:19], v[42:43], v[26:27], v[16:19]
	s_waitcnt vmcnt(22)
	v_mfma_f32_16x16x32_fp8_fp8 v[12:15], v[44:45], v[26:27], v[12:15]
	v_mfma_f32_16x16x32_fp8_fp8 v[8:11], v[46:47], v[26:27], v[8:11]
	v_cndmask_b32_e64 v27, 0, v144, s[8:9]
	v_cndmask_b32_e64 v26, 0, v31, s[8:9]
	s_waitcnt vmcnt(21)
	s_nop 0
	v_mfma_f32_16x16x32_fp8_fp8 v[20:23], v[56:57], v[26:27], v[20:23]
	v_mfma_f32_16x16x32_fp8_fp8 v[16:19], v[58:59], v[26:27], v[16:19]
	s_waitcnt vmcnt(20)
	v_mfma_f32_16x16x32_fp8_fp8 v[12:15], v[60:61], v[26:27], v[12:15]
	v_mfma_f32_16x16x32_fp8_fp8 v[8:11], v[62:63], v[26:27], v[8:11]
	v_cndmask_b32_e64 v27, 0, v144, s[10:11]
	v_cndmask_b32_e64 v26, 0, v31, s[10:11]
	s_waitcnt vmcnt(19)
	s_nop 0
	v_mfma_f32_16x16x32_fp8_fp8 v[20:23], v[74:75], v[26:27], v[20:23]
	v_mfma_f32_16x16x32_fp8_fp8 v[16:19], v[76:77], v[26:27], v[16:19]
	s_waitcnt vmcnt(18)
	v_mfma_f32_16x16x32_fp8_fp8 v[12:15], v[78:79], v[26:27], v[12:15]
	v_mfma_f32_16x16x32_fp8_fp8 v[8:11], v[80:81], v[26:27], v[8:11]
	v_cndmask_b32_e64 v27, 0, v144, s[12:13]
	v_cndmask_b32_e64 v26, 0, v31, s[12:13]
	s_waitcnt vmcnt(17)
	s_nop 0
	v_mfma_f32_16x16x32_fp8_fp8 v[20:23], v[106:107], v[26:27], v[20:23]
	v_mfma_f32_16x16x32_fp8_fp8 v[16:19], v[108:109], v[26:27], v[16:19]
	s_waitcnt vmcnt(16)
	v_mfma_f32_16x16x32_fp8_fp8 v[12:15], v[122:123], v[26:27], v[12:15]
	v_mfma_f32_16x16x32_fp8_fp8 v[8:11], v[124:125], v[26:27], v[8:11]
	v_fmac_f32_e32 v215, v212, v24
	s_add_i32 s24, s24, 32
	s_nop 0
	v_mov_b32_e32 v212, v215
	v_mov_b32_e32 v144, v213
	s_waitcnt vmcnt(15)
	v_mfma_f32_16x16x32_fp8_fp8 v[24:27], v[184:185], v[82:83], 0
	v_mov_b32_e32 v214, v165
	s_nop 0
	s_waitcnt vmcnt(14)
	v_mfma_f32_16x16x32_fp8_fp8 v[28:31], v[188:189], v[82:83], 0
	s_nop 0
	s_nop 0
	v_mfma_f32_16x16x32_fp8_fp8 v[24:27], v[186:187], v[104:105], v[24:27]
	v_mfma_f32_16x16x32_fp8_fp8 v[28:31], v[190:191], v[104:105], v[28:31]
	s_waitcnt vmcnt(13)
	v_mfma_f32_16x16x32_fp8_fp8 v[24:27], v[192:193], v[98:99], v[24:27]
	s_waitcnt vmcnt(12)
	v_mfma_f32_16x16x32_fp8_fp8 v[28:31], v[196:197], v[98:99], v[28:31]
	v_mfma_f32_16x16x32_fp8_fp8 v[24:27], v[194:195], v[110:111], v[24:27]
	v_mfma_f32_16x16x32_fp8_fp8 v[28:31], v[198:199], v[110:111], v[28:31]
	s_waitcnt vmcnt(11)
	v_mfma_f32_16x16x32_fp8_fp8 v[24:27], v[230:231], v[100:101], v[24:27]
	s_waitcnt vmcnt(10)
	v_mfma_f32_16x16x32_fp8_fp8 v[28:31], v[234:235], v[100:101], v[28:31]
	v_mfma_f32_16x16x32_fp8_fp8 v[24:27], v[232:233], v[120:121], v[24:27]
	v_mfma_f32_16x16x32_fp8_fp8 v[28:31], v[236:237], v[120:121], v[28:31]
	s_waitcnt vmcnt(9)
	v_mfma_f32_16x16x32_fp8_fp8 v[24:27], v[238:239], v[102:103], v[24:27]
	s_waitcnt vmcnt(8)
	v_mfma_f32_16x16x32_fp8_fp8 v[28:31], v[242:243], v[102:103], v[28:31]
	v_mfma_f32_16x16x32_fp8_fp8 v[24:27], v[240:241], v[126:127], v[24:27]
	v_mfma_f32_16x16x32_fp8_fp8 v[28:31], v[244:245], v[126:127], v[28:31]

; __device__ __forceinline__ void nsa_wave(CArgs* Ap, int l, int b, int g, int tq0, const LAS float* lut, LAS float* imp, int lane) {
;     ...
;             const long p8 = p_to_fp8(acc);
; #pragma unroll
;             for (int q2 = 0; q2 < 4; ++q2) { const long pm = (qi == q2) ? p8 : 0l; pv_acch8(Od, vq[q2], pm); }
;             if (more) {
; #pragma unroll
;                 for (int q2 = 0; q2 < 4; ++q2) load_vh8(vq[q2], Vs8 + (size_t)jn[q2] * 4096, h1, lane); }
;         }
;         float lt = st.l; lt += __shfl_xor(lt, 16); lt += __shfl_xor(lt, 32);
.Lsld_join:
	v_sub_f32_e32 v24, v144, v213
	v_cvt_pk_fp8_f32 v31, v216, v217
	v_mul_f32_e32 v24, 0x3fb8aa3b, v24
	v_cvt_pk_fp8_f32 v144, v220, v221
	v_exp_f32_e32 v24, v24
	v_cvt_pk_fp8_f32 v31, v218, v219 op_sel:[0,0,1]
	v_cvt_pk_fp8_f32 v144, v222, v223 op_sel:[0,0,1]
	v_pk_mul_f32 v[22:23], v[22:23], v[24:25] op_sel_hi:[1,0]
	v_pk_mul_f32 v[20:21], v[20:21], v[24:25] op_sel_hi:[1,0]
	v_cndmask_b32_e64 v27, 0, v144, s[6:7]
	v_cndmask_b32_e64 v26, 0, v31, s[6:7]
	v_pk_mul_f32 v[18:19], v[18:19], v[24:25] op_sel_hi:[1,0]
	v_pk_mul_f32 v[16:17], v[16:17], v[24:25] op_sel_hi:[1,0]
	v_pk_mul_f32 v[14:15], v[14:15], v[24:25] op_sel_hi:[1,0]
	v_pk_mul_f32 v[12:13], v[12:13], v[24:25] op_sel_hi:[1,0]
	v_pk_mul_f32 v[10:11], v[10:11], v[24:25] op_sel_hi:[1,0]
	v_pk_mul_f32 v[8:9], v[8:9], v[24:25] op_sel_hi:[1,0]
	s_waitcnt vmcnt(7)
	s_nop 0
	v_mfma_f32_16x16x32_fp8_fp8 v[20:23], v[134:135], v[26:27], v[20:23]
	v_mfma_f32_16x16x32_fp8_fp8 v[16:19], v[136:137], v[26:27], v[16:19]
	s_waitcnt vmcnt(6)
	v_mfma_f32_16x16x32_fp8_fp8 v[12:15], v[138:139], v[26:27], v[12:15]
	v_mfma_f32_16x16x32_fp8_fp8 v[8:11], v[140:141], v[26:27], v[8:11]
	v_cndmask_b32_e64 v27, 0, v144, s[8:9]
	v_cndmask_b32_e64 v26, 0, v31, s[8:9]
	s_waitcnt vmcnt(5)
	s_nop 0
	v_mfma_f32_16x16x32_fp8_fp8 v[20:23], v[152:153], v[26:27], v[20:23]
	v_mfma_f32_16x16x32_fp8_fp8 v[16:19], v[154:155], v[26:27], v[16:19]
	s_waitcnt vmcnt(4)
	v_mfma_f32_16x16x32_fp8_fp8 v[12:15], v[156:157], v[26:27], v[12:15]
	v_mfma_f32_16x16x32_fp8_fp8 v[8:11], v[158:159], v[26:27], v[8:11]
	v_cndmask_b32_e64 v27, 0, v144, s[10:11]
	v_cndmask_b32_e64 v26, 0, v31, s[10:11]
	s_waitcnt vmcnt(3)
	s_nop 0
	v_mfma_f32_16x16x32_fp8_fp8 v[20:23], v[160:161], v[26:27], v[20:23]
	v_mfma_f32_16x16x32_fp8_fp8 v[16:19], v[162:163], v[26:27], v[16:19]
	s_waitcnt vmcnt(2)
	v_mfma_f32_16x16x32_fp8_fp8 v[12:15], v[246:247], v[26:27], v[12:15]
	v_mfma_f32_16x16x32_fp8_fp8 v[8:11], v[248:249], v[26:27], v[8:11]
	v_cndmask_b32_e64 v27, 0, v144, s[12:13]
	v_cndmask_b32_e64 v26, 0, v31, s[12:13]
	s_waitcnt vmcnt(1)
	s_nop 0
	v_mfma_f32_16x16x32_fp8_fp8 v[20:23], v[0:1], v[26:27], v[20:23]
	v_mfma_f32_16x16x32_fp8_fp8 v[16:19], v[2:3], v[26:27], v[16:19]
	s_waitcnt vmcnt(0)
	v_mfma_f32_16x16x32_fp8_fp8 v[12:15], v[4:5], v[26:27], v[12:15]
	v_mfma_f32_16x16x32_fp8_fp8 v[8:11], v[6:7], v[26:27], v[8:11]
	v_fmac_f32_e32 v215, v212, v24
	s_add_i32 s24, s24, 32
	s_nop 0
	v_mov_b32_e32 v212, v215
	v_mov_b32_e32 v144, v213
	s_nop 7
	ds_read_b128 v[0:3], v93 offset:4096
	ds_read_b128 v[4:7], v93 offset:5120
	s_branch .LBB0_1280
